# v35
# speedup vs baseline: 1.0194x; 1.0094x over previous
; DI f32x16 mfma32(bf16x8 a, bf16x8 b, f32x16 c) { return __builtin_amdgcn_mfma_f32_32x32x16_bf16(a, b, c, 0, 0, 0); }
; DI int crow(int i, int h) { return (i & 3) + 8 * (i >> 2) + 4 * h; }
; DI f32x16 zero16() { f32x16 z; for (int i = 0; i < 16; ++i) z[i] = 0.f; return z; }
; template <int D_> DI f32x16 qk_tile(const bf16* Kp, const bf16x8 (&qf)[D_ / 16]) {
;     f32x16 x = zero16();
; #pragma unroll
;     for (int ks = 0; ks < D_ / 16; ++ks) { const bf16x8 kf = *(const bf16x8*)(Kp + 16 * ks); x = mfma32(kf, qf[ks], x); }
;     return x;
; }
; DI void swa_item(const Ctx& c, const float* sinks, int qt, int hq, int lane) {
;     ...
;     for (int key0 = kstart; key0 <= t0; key0 += 32) {
;         f32x16 x = qk_tile<64>(c.P + (size_t)(key0 + r) * PP + 2048 + g * 64 + 8 * h, qf);
; #pragma unroll
;         for (int i = 0; i < 16; ++i) { const int dist = t - (key0 + crow(i, h)); x[i] = ((unsigned)dist < 128u) ? x[i] * sc2 - slope2 * (float)dist : -INFINITY; }
;         osm_step<2>(x, m, l, o);
.LBB0_1162:
	v_mov_b32_e32 v78, v35
	v_mov_b32_e32 v79, v34
	v_add_u32_e32 v36, s41, v151
	v_mov_b64_e32 v[34:35], s[26:27]
	v_mad_i64_i32 v[34:35], s[42:43], v36, s56, v[34:35]
	v_lshl_add_u64 v[34:35], v[34:35], 0, s[34:35]
	v_lshl_add_u64 v[34:35], v[122:123], 1, v[34:35]
	v_lshl_add_u64 v[76:77], v[34:35], 0, s[68:69]
	v_add_co_u32_e32 v34, vcc, s0, v34
	global_load_dwordx4 v[72:75], v[76:77], off offset:32
	s_nop 0
	v_addc_co_u32_e32 v35, vcc, 0, v35, vcc
	global_load_dwordx4 v[34:37], v[34:35], off
	global_load_dwordx4 v[198:201], v[76:77], off offset:64
	global_load_dwordx4 v[202:205], v[76:77], off offset:96
	s_ashr_i32 s42, s41, 5
	s_ashr_i32 s43, s42, 31
	s_lshl_b64 s[42:43], s[42:43], 16
	v_lshl_add_u64 v[206:207], v[68:69], 0, s[42:43]
	global_load_dwordx4 v[208:211], v[206:207], off
	global_load_dwordx4 v[212:215], v[206:207], off offset:16
	global_load_dwordx4 v[216:219], v[206:207], off offset:2048
	global_load_dwordx4 v[220:223], v[206:207], off offset:2064
	s_waitcnt vmcnt(6)
	v_mfma_f32_32x32x16_bf16 v[34:49], v[34:37], v[50:53], 0
	v_mfma_f32_32x32x16_bf16 v[34:49], v[72:75], v[54:57], v[34:49]
	s_waitcnt vmcnt(5)
	v_mfma_f32_32x32x16_bf16 v[34:49], v[198:201], v[58:61], v[34:49]
	s_waitcnt vmcnt(4)
	v_mfma_f32_32x32x16_bf16 v[34:49], v[202:205], v[62:65], v[34:49]
	v_add_u32_e32 v74, v151, v71
	v_cvt_f32_u32_e32 v171, v74
	v_cmp_gt_u32_e32 vcc, s91, v74
	v_subrev_u32_e32 v71, 32, v71
	s_nop 7
	v_mov_b32_e32 v66, v34
	v_pk_mul_f32 v[72:73], v[66:67], v[170:171]
	v_mov_b32_e32 v66, v35
	v_sub_f32_e32 v34, v72, v73
	v_cndmask_b32_e32 v72, v237, v34, vcc
	v_add_u32_e32 v34, -1, v74
	v_cvt_f32_u32_e32 v171, v34
	v_cmp_gt_u32_e32 vcc, s91, v34
	v_pk_mul_f32 v[34:35], v[66:67], v[170:171]
	s_nop 0
	v_sub_f32_e32 v34, v34, v35
	v_cndmask_b32_e32 v73, v237, v34, vcc
	v_add_u32_e32 v34, -2, v74
	v_cvt_f32_u32_e32 v171, v34
	v_mov_b32_e32 v66, v36
	v_cmp_gt_u32_e32 vcc, s91, v34
	v_pk_mul_f32 v[34:35], v[66:67], v[170:171]
	s_nop 0
	v_sub_f32_e32 v34, v34, v35
	v_cndmask_b32_e32 v75, v237, v34, vcc
	v_add_u32_e32 v34, -3, v74
	v_cvt_f32_u32_e32 v171, v34
	v_mov_b32_e32 v66, v37
	v_cmp_gt_u32_e32 vcc, s91, v34
	v_pk_mul_f32 v[34:35], v[66:67], v[170:171]
	s_nop 0
	v_sub_f32_e32 v34, v34, v35
	v_cndmask_b32_e32 v76, v237, v34, vcc
	v_add_u32_e32 v34, -8, v74
	v_cvt_f32_u32_e32 v171, v34
	v_mov_b32_e32 v66, v38
	v_cmp_gt_u32_e32 vcc, s91, v34
	v_pk_mul_f32 v[34:35], v[66:67], v[170:171]
	s_nop 0
	v_sub_f32_e32 v34, v34, v35
	v_cndmask_b32_e32 v77, v237, v34, vcc
	v_add_u32_e32 v34, -9, v74
	v_cvt_f32_u32_e32 v171, v34
	v_mov_b32_e32 v66, v39
	v_cmp_gt_u32_e32 vcc, s91, v34
	v_pk_mul_f32 v[34:35], v[66:67], v[170:171]
	s_nop 0
	v_sub_f32_e32 v34, v34, v35
	v_cndmask_b32_e32 v80, v237, v34, vcc
	v_add_u32_e32 v34, -10, v74
	v_cvt_f32_u32_e32 v171, v34
	v_mov_b32_e32 v66, v40
	v_cmp_gt_u32_e32 vcc, s91, v34
	v_pk_mul_f32 v[34:35], v[66:67], v[170:171]
	s_nop 0
	v_sub_f32_e32 v34, v34, v35
	v_cndmask_b32_e32 v81, v237, v34, vcc
	v_add_u32_e32 v34, -11, v74
	v_cvt_f32_u32_e32 v171, v34
	v_mov_b32_e32 v66, v41
	v_cmp_gt_u32_e32 vcc, s91, v34
	v_pk_mul_f32 v[34:35], v[66:67], v[170:171]
	s_nop 0
	v_sub_f32_e32 v34, v34, v35
	v_cndmask_b32_e32 v82, v237, v34, vcc
	v_add_u32_e32 v34, -16, v74
	v_cvt_f32_u32_e32 v171, v34
	v_mov_b32_e32 v66, v42
	v_cmp_gt_u32_e32 vcc, s91, v34
	v_pk_mul_f32 v[34:35], v[66:67], v[170:171]
	s_nop 0
	v_sub_f32_e32 v34, v34, v35
	v_cndmask_b32_e32 v83, v237, v34, vcc
	v_subrev_u32_e32 v34, 17, v74
	v_cvt_f32_u32_e32 v171, v34
	v_mov_b32_e32 v66, v43
	v_cmp_gt_u32_e32 vcc, s91, v34
	v_pk_mul_f32 v[34:35], v[66:67], v[170:171]
	s_nop 0
	v_sub_f32_e32 v34, v34, v35
	v_cndmask_b32_e32 v84, v237, v34, vcc
	v_subrev_u32_e32 v34, 18, v74
	v_cvt_f32_u32_e32 v171, v34
	v_mov_b32_e32 v66, v44
	v_cmp_gt_u32_e32 vcc, s91, v34
	v_pk_mul_f32 v[34:35], v[66:67], v[170:171]
	s_nop 0
	v_sub_f32_e32 v34, v34, v35
	v_cndmask_b32_e32 v85, v237, v34, vcc
	v_subrev_u32_e32 v34, 19, v74
	v_cvt_f32_u32_e32 v171, v34
	v_mov_b32_e32 v66, v45
	v_cmp_gt_u32_e32 vcc, s91, v34
	v_pk_mul_f32 v[34:35], v[66:67], v[170:171]
	s_nop 0
	v_sub_f32_e32 v34, v34, v35
	v_cndmask_b32_e32 v86, v237, v34, vcc
	v_subrev_u32_e32 v34, 24, v74
	v_cvt_f32_u32_e32 v171, v34
	v_mov_b32_e32 v66, v46
	v_cmp_gt_u32_e32 vcc, s91, v34
	v_pk_mul_f32 v[34:35], v[66:67], v[170:171]
	s_nop 0
	v_sub_f32_e32 v34, v34, v35
	v_cndmask_b32_e32 v87, v237, v34, vcc
	v_subrev_u32_e32 v34, 25, v74
	v_cvt_f32_u32_e32 v171, v34
	v_mov_b32_e32 v66, v47
	v_cmp_gt_u32_e32 vcc, s91, v34
	v_pk_mul_f32 v[34:35], v[66:67], v[170:171]
	s_nop 0
	v_sub_f32_e32 v34, v34, v35
	v_cndmask_b32_e32 v88, v237, v34, vcc
	v_subrev_u32_e32 v34, 26, v74
	v_cvt_f32_u32_e32 v171, v34
	v_mov_b32_e32 v66, v48
	v_cmp_gt_u32_e32 vcc, s91, v34
	v_pk_mul_f32 v[34:35], v[66:67], v[170:171]
	s_nop 0
	v_sub_f32_e32 v34, v34, v35
	v_cndmask_b32_e32 v89, v237, v34, vcc
	v_subrev_u32_e32 v34, 27, v74
	v_cvt_f32_u32_e32 v171, v34
	v_mov_b32_e32 v66, v49
	v_cmp_gt_u32_e32 vcc, s91, v34
	v_pk_mul_f32 v[34:35], v[66:67], v[170:171]
	s_nop 0
	v_sub_f32_e32 v34, v34, v35
	v_cndmask_b32_e32 v35, v237, v34, vcc
	v_max_f32_e32 v34, v72, v73
	v_max3_f32 v34, v34, v75, v76
	v_max3_f32 v34, v34, v77, v80
	v_max3_f32 v34, v34, v81, v82
	v_max3_f32 v34, v34, v83, v84
	v_max3_f32 v34, v34, v85, v86
	v_max3_f32 v34, v34, v87, v88
	v_max3_f32 v34, v34, v89, v35
	v_mov_b32_e32 v36, v34
	s_nop 1
	v_permlane32_swap_b32_e32 v34, v36
	v_max3_f32 v34, v79, v34, v36
	v_sub_f32_e32 v36, v72, v34
	v_exp_f32_e32 v36, v36
	v_sub_f32_e32 v37, v73, v34
; DI float ex2(float x) { return __builtin_amdgcn_exp2f(x); }
; DI void both_halves(float x, float& lo, float& hi) { auto rr = __builtin_amdgcn_permlane32_swap(__float_as_uint(x), __float_as_uint(x), false, false); lo = __uint_as_float(rr[0]); hi = __uint_as_float(rr[1]); }
; template <int NDB> DI void osm_step(f32x16& x, float& m, float& l, f32x16 (&o)[NDB]) {
;     float tm = x[0];
; #pragma unroll
;     for (int i = 1; i < 16; ++i) tm = fmaxf(tm, x[i]);
;     float lo, hi; both_halves(tm, lo, hi); tm = fmaxf(lo, hi);
;     const float mn = fmaxf(m, tm), alpha = ex2(m - mn); m = mn;
;     float ps = 0.f;
; #pragma unroll
;     for (int i = 0; i < 16; ++i) { x[i] = ex2(x[i] - mn); ps += x[i]; }
;     l = l * alpha + ps;
; #pragma unroll
;     for (int db = 0; db < NDB; ++db) o[db] = o[db] * alpha;
; }
; DI void swa_item(const Ctx& c, const float* sinks, int qt, int hq, int lane) {
;     ...
;         pv_tile_p<64>(c.VT + ((size_t)(key0 >> 5) * 1024 + g * 64 + r) * 32 + 16 * h, x, o);
;     }
;     float lo, hi; both_halves(l, lo, hi);
;     const float lt = lo + hi + ex2(sink2 - m);
;     store_o<2>(c.Y + (size_t)t * 512 + hq * 64, o, 1.f / lt, h);
	v_exp_f32_e32 v37, v37
	v_sub_f32_e32 v35, v35, v34
	v_add_f32_e32 v38, 0, v36
	v_sub_f32_e32 v74, v79, v34
	v_add_f32_e32 v39, v37, v38
	v_sub_f32_e32 v38, v75, v34
	v_exp_f32_e32 v38, v38
	v_exp_f32_e32 v74, v74
	v_cvt_pk_bf16_f32 v36, v36, v37
	v_add_f32_e32 v40, v38, v39
	v_sub_f32_e32 v39, v76, v34
	v_exp_f32_e32 v39, v39
	v_pk_mul_f32 v[16:17], v[16:17], v[74:75] op_sel_hi:[1,0]
	v_pk_mul_f32 v[14:15], v[14:15], v[74:75] op_sel_hi:[1,0]
	v_pk_mul_f32 v[12:13], v[12:13], v[74:75] op_sel_hi:[1,0]
	v_add_f32_e32 v41, v39, v40
	v_sub_f32_e32 v40, v77, v34
	v_exp_f32_e32 v40, v40
	v_lshl_add_u64 v[76:77], v[68:69], 0, s[42:43]
	v_pk_mul_f32 v[10:11], v[10:11], v[74:75] op_sel_hi:[1,0]
	v_pk_mul_f32 v[8:9], v[8:9], v[74:75] op_sel_hi:[1,0]
	v_add_f32_e32 v42, v40, v41
	v_sub_f32_e32 v41, v80, v34
	v_exp_f32_e32 v41, v41
	v_pk_mul_f32 v[6:7], v[6:7], v[74:75] op_sel_hi:[1,0]
	v_pk_mul_f32 v[4:5], v[4:5], v[74:75] op_sel_hi:[1,0]
	v_pk_mul_f32 v[2:3], v[2:3], v[74:75] op_sel_hi:[1,0]
	v_add_f32_e32 v43, v41, v42
	v_sub_f32_e32 v42, v81, v34
	v_exp_f32_e32 v42, v42
	v_pk_mul_f32 v[32:33], v[32:33], v[74:75] op_sel_hi:[1,0]
	v_pk_mul_f32 v[30:31], v[30:31], v[74:75] op_sel_hi:[1,0]
	v_pk_mul_f32 v[28:29], v[28:29], v[74:75] op_sel_hi:[1,0]
	v_add_f32_e32 v44, v42, v43
	v_sub_f32_e32 v43, v82, v34
	v_exp_f32_e32 v43, v43
	v_pk_mul_f32 v[26:27], v[26:27], v[74:75] op_sel_hi:[1,0]
	v_pk_mul_f32 v[24:25], v[24:25], v[74:75] op_sel_hi:[1,0]
	v_pk_mul_f32 v[22:23], v[22:23], v[74:75] op_sel_hi:[1,0]
	v_add_f32_e32 v45, v43, v44
	v_sub_f32_e32 v44, v83, v34
	v_exp_f32_e32 v44, v44
	v_pk_mul_f32 v[20:21], v[20:21], v[74:75] op_sel_hi:[1,0]
	v_pk_mul_f32 v[18:19], v[18:19], v[74:75] op_sel_hi:[1,0]
	v_cvt_pk_bf16_f32 v37, v38, v39
	v_add_f32_e32 v46, v44, v45
	v_sub_f32_e32 v45, v84, v34
	v_exp_f32_e32 v45, v45
	v_cvt_pk_bf16_f32 v38, v40, v41
	v_cvt_pk_bf16_f32 v39, v42, v43
	s_add_i32 s42, s41, 32
	v_add_f32_e32 v47, v45, v46
	v_sub_f32_e32 v46, v85, v34
	v_exp_f32_e32 v46, v46
	v_cvt_pk_bf16_f32 v40, v44, v45
	s_cmp_lt_i32 s41, s9
	s_mov_b32 s41, s42
	v_add_f32_e32 v48, v46, v47
	v_sub_f32_e32 v47, v86, v34
	v_exp_f32_e32 v47, v47
	s_nop 0
	v_add_f32_e32 v49, v47, v48
	v_sub_f32_e32 v48, v87, v34
	v_exp_f32_e32 v48, v48
	v_cvt_pk_bf16_f32 v41, v46, v47
	v_add_f32_e32 v66, v48, v49
	v_sub_f32_e32 v49, v88, v34
	v_exp_f32_e32 v49, v49
	s_nop 0
	v_add_f32_e32 v72, v49, v66
	v_sub_f32_e32 v66, v89, v34
	v_exp_f32_e32 v66, v66
	v_cvt_pk_bf16_f32 v42, v48, v49
	v_add_f32_e32 v73, v66, v72
	v_exp_f32_e32 v72, v35
	s_nop 0
	v_add_f32_e32 v35, v72, v73
	v_fmac_f32_e32 v35, v78, v74
	v_cvt_pk_bf16_f32 v43, v66, v72
	s_waitcnt vmcnt(3)
	v_mfma_f32_32x32x16_bf16 v[2:17], v[208:211], v[36:39], v[2:17]
	s_waitcnt vmcnt(2)
	v_mfma_f32_32x32x16_bf16 v[2:17], v[212:215], v[40:43], v[2:17]
	s_waitcnt vmcnt(1)
	v_mfma_f32_32x32x16_bf16 v[18:33], v[216:219], v[36:39], v[18:33]
	s_waitcnt vmcnt(0)
	v_mfma_f32_32x32x16_bf16 v[18:33], v[220:223], v[40:43], v[18:33]
	s_cbranch_scc1 .LBB0_1162
	v_sub_f32_e32 v34, v70, v34
	v_exp_f32_e32 v34, v34
	v_mov_b32_e32 v36, v35
	s_nop 1
	v_permlane32_swap_b32_e32 v35, v36
	v_add_f32_e32 v35, v35, v36
	v_add_f32_e32 v36, v34, v35
	v_lshlrev_b64 v[34:35], 10, v[0:1]
	s_lshl_b32 s34, s8, 1
	v_div_scale_f32 v0, s[8:9], v36, v36, 1.0
	v_rcp_f32_e32 v37, v0
	v_lshl_add_u64 v[34:35], s[12:13], 0, v[34:35]
	v_lshl_add_u64 v[34:35], v[34:35], 0, s[34:35]
	v_lshl_add_u64 v[34:35], v[124:125], 1, v[34:35]
	v_fma_f32 v38, -v0, v37, 1.0
	v_fmac_f32_e32 v37, v38, v37
	v_div_scale_f32 v38, vcc, 1.0, v36, 1.0
	v_mul_f32_e32 v39, v38, v37
	v_fma_f32 v40, -v0, v39, v38
	v_fmac_f32_e32 v39, v40, v37
	v_fma_f32 v0, -v0, v39, v38
	v_div_fmas_f32 v0, v0, v37, v39
	v_div_fixup_f32 v0, v0, v36, 1.0
	v_pk_mul_f32 v[2:3], v[2:3], v[0:1] op_sel_hi:[1,0]
	v_pk_mul_f32 v[4:5], v[4:5], v[0:1] op_sel_hi:[1,0]
	v_cvt_pk_bf16_f32 v2, v2, v3
	v_cvt_pk_bf16_f32 v3, v4, v5
	global_store_dwordx2 v[34:35], v[2:3], off
	v_pk_mul_f32 v[2:3], v[6:7], v[0:1] op_sel_hi:[1,0]
	v_pk_mul_f32 v[4:5], v[8:9], v[0:1] op_sel_hi:[1,0]
	v_cvt_pk_bf16_f32 v2, v2, v3
	v_cvt_pk_bf16_f32 v3, v4, v5
	global_store_dwordx2 v[34:35], v[2:3], off offset:16
	v_pk_mul_f32 v[2:3], v[10:11], v[0:1] op_sel_hi:[1,0]
	v_pk_mul_f32 v[4:5], v[12:13], v[0:1] op_sel_hi:[1,0]
	v_cvt_pk_bf16_f32 v2, v2, v3
	v_cvt_pk_bf16_f32 v3, v4, v5
	global_store_dwordx2 v[34:35], v[2:3], off offset:32
	v_pk_mul_f32 v[2:3], v[14:15], v[0:1] op_sel_hi:[1,0]
	v_pk_mul_f32 v[4:5], v[16:17], v[0:1] op_sel_hi:[1,0]
	v_cvt_pk_bf16_f32 v2, v2, v3
	v_cvt_pk_bf16_f32 v3, v4, v5
	global_store_dwordx2 v[34:35], v[2:3], off offset:48
	v_pk_mul_f32 v[2:3], v[18:19], v[0:1] op_sel_hi:[1,0]
	v_pk_mul_f32 v[4:5], v[20:21], v[0:1] op_sel_hi:[1,0]
	v_cvt_pk_bf16_f32 v2, v2, v3
	v_cvt_pk_bf16_f32 v3, v4, v5
	global_store_dwordx2 v[34:35], v[2:3], off offset:64
	v_pk_mul_f32 v[2:3], v[22:23], v[0:1] op_sel_hi:[1,0]
	v_pk_mul_f32 v[4:5], v[24:25], v[0:1] op_sel_hi:[1,0]
	v_cvt_pk_bf16_f32 v2, v2, v3
	v_cvt_pk_bf16_f32 v3, v4, v5
	global_store_dwordx2 v[34:35], v[2:3], off offset:80
	v_pk_mul_f32 v[2:3], v[26:27], v[0:1] op_sel_hi:[1,0]
	v_pk_mul_f32 v[4:5], v[28:29], v[0:1] op_sel_hi:[1,0]
	v_cvt_pk_bf16_f32 v2, v2, v3
	v_cvt_pk_bf16_f32 v3, v4, v5
	global_store_dwordx2 v[34:35], v[2:3], off offset:96
	v_pk_mul_f32 v[2:3], v[30:31], v[0:1] op_sel_hi:[1,0]
	v_pk_mul_f32 v[4:5], v[32:33], v[0:1] op_sel_hi:[1,0]
	v_cvt_pk_bf16_f32 v2, v2, v3
	v_cvt_pk_bf16_f32 v3, v4, v5
	s_mov_b64 s[8:9], 0
	s_mov_b32 s44, s19
	global_store_dwordx2 v[34:35], v[2:3], off offset:112
